# attention: first K/V tile + Q fragments of the next (b,h,q-block) requested at loop exit, before the normalisation / output stores
# speedup vs baseline: 1.0174x; 1.0022x over previous
; #define wave (__builtin_amdgcn_readfirstlane((int)(threadIdx.x >> 6)))
; __device__ __forceinline__ void attn_phase(LAS unsigned char* lds, const bf16_t* __restrict__ Q, const bf16_t* __restrict__ KN, const bf16_t* __restrict__ KR,
;                                            const bf16_t* __restrict__ VT, bf16_t* AO, int vcu, int G, int tid, int lane, int wave) {
;     ...
;     for (int p = vcu; p < 512; p += G) {
; #pragma unroll 1
;         for (int half = 0; half < 2; ++half) {
;             const int bh = p >> 3, pp = p & 7, qb = half ? 15 - pp : pp, b = bh >> 3, h = bh & 7;
;             const size_t rowbase = (size_t)b * SEQ;
;             const int qrow0 = qb * 256 + wave * 32, qc = qrow0 >> 6, NT2 = 2 * qb + 2;
;             bf16x8 qf[6];
;             { const bf16_t* qp = Q + (rowbase + qrow0 + r32) * NQ + h * 96 + 8 * hi;
; #pragma unroll
;               for (int ks = 0; ks < 6; ++ks) qf[ks] = *(const bf16x8*)(qp + 16 * ks); }
;             const char* kbase = (const char*)(KN + rowbase * NKN + h * 64); const unsigned koff = (unsigned)(key_l * NKN + 8 * kc) * 2u;
;             const char* rbase = (const char*)(KR + rowbase * 32); const unsigned roff = (unsigned)(key_r * 32 + 8 * rc) * 2u;
;             const char* vbase = (const char*)(VT + (size_t)(h * 64) * MTOK + rowbase); const unsigned voff = (unsigned)((size_t)vd * MTOK + 8 * vc) * 2u;
;     ...
;             const float l = l_run + __shfl_xor(l_run, 32);
;             const float inv = 1.0f / l;
;             bf16_t* op = AO + (rowbase + qrow0 + r32) * DM + h * 64 + 8 * hi;
.LBB0_532:
	s_nop 3
	ds_bpermute_b32 v1, v224, v227
	v_lshlrev_b64 v[34:35], 11, v[216:217]
	v_lshl_add_u64 v[36:37], v[214:215], 0, v[34:35]
	s_mov_b32 s42, 0
	s_and_b64 vcc, exec, s[12:13]
	s_cbranch_vccz .Lat_nx_same
	s_add_i32 s22, s22, s28
	s_cmpk_gt_i32 s22, 0x1ff
	s_cbranch_scc1 .Lat_nx_none
	s_ashr_i32 s6, s22, 6
	s_and_b32 s23, s22, 7
	s_ashr_i32 s7, s6, 31
	s_xor_b32 s31, s23, 15
	s_bfe_u32 s26, s22, 0x30003
	s_lshl_b64 s[12:13], s[6:7], 12
	s_lshl_b64 s[10:11], s[6:7], 22
	s_mul_i32 s8, s26, 0xc0
	s_add_u32 s10, s16, s10
	v_lshl_add_u64 v[206:207], v[196:197], 0, s[8:9]
	s_addc_u32 s11, s17, s11
	s_lshl_b32 s8, s26, 7
	s_add_u32 s10, s10, s8
	s_addc_u32 s11, s11, 0
	s_lshl_b64 s[14:15], s[6:7], 18
	s_lshl_b32 s26, s26, 22
	s_add_u32 s26, s18, s26
	s_addc_u32 s27, s19, 0
	s_lshl_b64 s[6:7], s[6:7], 13
	s_add_u32 s6, s26, s6
	s_addc_u32 s7, s27, s7
	v_lshl_add_u64 v[208:209], v[204:205], 0, s[14:15]
	v_lshl_add_u64 v[210:211], s[6:7], 0, v[200:201]
	v_mov_b32_e32 v213, s13
	v_or_b32_e32 v212, s12, v194
	v_lshl_add_u64 v[214:215], v[202:203], 0, s[8:9]
	s_mov_b64 s[6:7], -1
	s_branch .Lat_nx_issue

; #define wave (__builtin_amdgcn_readfirstlane((int)(threadIdx.x >> 6)))
; __device__ __forceinline__ void attn_phase(LAS unsigned char* lds, const bf16_t* __restrict__ Q, const bf16_t* __restrict__ KN, const bf16_t* __restrict__ KR,
;                                            const bf16_t* __restrict__ VT, bf16_t* AO, int vcu, int G, int tid, int lane, int wave) {
;     ...
;             const int bh = p >> 3, pp = p & 7, qb = half ? 15 - pp : pp, b = bh >> 3, h = bh & 7;
;             const size_t rowbase = (size_t)b * SEQ;
;             const int qrow0 = qb * 256 + wave * 32, qc = qrow0 >> 6, NT2 = 2 * qb + 2;
;             bf16x8 qf[6];
;             { const bf16_t* qp = Q + (rowbase + qrow0 + r32) * NQ + h * 96 + 8 * hi;
; #pragma unroll
;               for (int ks = 0; ks < 6; ++ks) qf[ks] = *(const bf16x8*)(qp + 16 * ks); }
;             const char* kbase = (const char*)(KN + rowbase * NKN + h * 64); const unsigned koff = (unsigned)(key_l * NKN + 8 * kc) * 2u;
;             const char* rbase = (const char*)(KR + rowbase * 32); const unsigned roff = (unsigned)(key_r * 32 + 8 * rc) * 2u;
;             const char* vbase = (const char*)(VT + (size_t)(h * 64) * MTOK + rowbase); const unsigned voff = (unsigned)((size_t)vd * MTOK + 8 * vc) * 2u;
;             const int kdst = (key_l * KP + 8 * kc) * 2, rdst = (key_r * KP + 64 + 8 * rc) * 2, vdst = KBUF + (vd * VP + 8 * vc) * 2;
;             u32x4 gk0, gk1, gr, gv0, gv1;
;             gk0 = *(const u32x4*)(kbase + koff); gk1 = *(const u32x4*)(kbase + 64 * NKN * 2 + koff); gr = *(const u32x4*)(rbase + roff); gv0 = *(const u32x4*)(vbase + voff); gv1 = *(const u32x4*)(vbase + 128 + voff);
;     ...
;             const float l = l_run + __shfl_xor(l_run, 32);
;             const float inv = 1.0f / l;
;             bf16_t* op = AO + (rowbase + qrow0 + r32) * DM + h * 64 + 8 * hi;
; #pragma unroll
;             for (int blk_ = 0; blk_ < 2; ++blk_) {
; #pragma unroll
;                 for (int k2 = 0; k2 < 2; ++k2) {
;                     const int g0 = 2 * k2, g1 = 2 * k2 + 1;
;                     unsigned x0, x1, y0, y1;
;                     if (blk_ == 0) { x0 = pk2(o0[4 * g0] * inv, o0[4 * g0 + 1] * inv); x1 = pk2(o0[4 * g0 + 2] * inv, o0[4 * g0 + 3] * inv); y0 = pk2(o0[4 * g1] * inv, o0[4 * g1 + 1] * inv); y1 = pk2(o0[4 * g1 + 2] * inv, o0[4 * g1 + 3] * inv); }
.Lat_nx_issue:
	s_xor_b64 s[12:13], s[6:7], -1
	s_and_b64 s[6:7], s[6:7], exec
	s_cselect_b32 s14, s23, s31
	s_lshl_b32 s6, s14, 8
	s_add_i32 s8, s6, s20
	v_lshl_add_u64 v[216:217], v[212:213], 0, s[8:9]
	s_lshl_b32 s36, s14, 1
	global_load_dwordx4 v[228:231], v198, s[10:11]
	s_add_u32 s14, s10, 0x10000
	s_addc_u32 s15, s11, 0
	v_mad_u64_u32 v[250:251], s[6:7], v216, s21, v[206:207]
	global_load_dwordx4 v[232:235], v198, s[14:15]
	v_mad_i32_i24 v251, v217, s21, v251
	global_load_dwordx4 v[236:239], v[208:209], off
	global_load_dwordx4 v[240:243], v[210:211], off
	global_load_dwordx4 v[244:247], v[210:211], off offset:128
	global_load_dwordx4 v[114:117], v[250:251], off
	global_load_dwordx4 v[118:121], v[250:251], off offset:32
	global_load_dwordx4 v[122:125], v[250:251], off offset:64
	global_load_dwordx4 v[126:129], v[250:251], off offset:96
	global_load_dwordx4 v[130:133], v[250:251], off offset:128
	global_load_dwordx4 v[134:137], v[250:251], off offset:160
	s_mov_b32 s42, 1
.Lat_nx_none:
	s_waitcnt lgkmcnt(0)
	v_add_f32_e32 v1, v227, v1
	v_div_scale_f32 v40, s[6:7], v1, v1, 1.0
	v_rcp_f32_e32 v41, v40
	v_div_scale_f32 v38, vcc, 1.0, v1, 1.0
	v_fma_f32 v39, -v40, v41, 1.0
	v_fmac_f32_e32 v41, v39, v41
	v_mul_f32_e32 v39, v38, v41
	v_fma_f32 v42, -v40, v39, v38
	v_fmac_f32_e32 v39, v42, v41
	v_fma_f32 v38, -v40, v39, v38
	v_div_fmas_f32 v38, v38, v41, v39
	v_div_fixup_f32 v42, v38, v1, 1.0
	s_nop 0
	v_pk_mul_f32 v[44:45], v[8:9], v[42:43] op_sel_hi:[1,0]
	v_pk_mul_f32 v[46:47], v[6:7], v[42:43] op_sel_hi:[1,0]
	v_pk_mul_f32 v[48:49], v[4:5], v[42:43] op_sel_hi:[1,0]
	v_pk_mul_f32 v[50:51], v[2:3], v[42:43] op_sel_hi:[1,0]
	v_cvt_pk_bf16_f32 v55, v44, v45
	v_cvt_pk_bf16_f32 v54, v46, v47
	v_cvt_pk_bf16_f32 v53, v48, v49
	v_cvt_pk_bf16_f32 v52, v50, v51
	s_nop 1
	v_permlane32_swap_b32_e32 v52, v54
	v_permlane32_swap_b32_e32 v53, v55
	global_store_dwordx4 v[36:37], v[52:55], off
	v_pk_mul_f32 v[44:45], v[16:17], v[42:43] op_sel_hi:[1,0]
	v_pk_mul_f32 v[46:47], v[14:15], v[42:43] op_sel_hi:[1,0]
	v_pk_mul_f32 v[48:49], v[12:13], v[42:43] op_sel_hi:[1,0]
	v_pk_mul_f32 v[50:51], v[10:11], v[42:43] op_sel_hi:[1,0]
	v_cvt_pk_bf16_f32 v55, v44, v45
	v_cvt_pk_bf16_f32 v54, v46, v47
	v_cvt_pk_bf16_f32 v53, v48, v49
	v_cvt_pk_bf16_f32 v52, v50, v51
	s_nop 1
	v_permlane32_swap_b32_e32 v52, v54
	v_permlane32_swap_b32_e32 v53, v55
	global_store_dwordx4 v[36:37], v[52:55], off offset:32
	v_pk_mul_f32 v[44:45], v[24:25], v[42:43] op_sel_hi:[1,0]
	v_pk_mul_f32 v[46:47], v[22:23], v[42:43] op_sel_hi:[1,0]
	v_pk_mul_f32 v[48:49], v[20:21], v[42:43] op_sel_hi:[1,0]
	v_pk_mul_f32 v[50:51], v[18:19], v[42:43] op_sel_hi:[1,0]
	v_cvt_pk_bf16_f32 v55, v44, v45
	v_cvt_pk_bf16_f32 v54, v46, v47
	v_cvt_pk_bf16_f32 v53, v48, v49
	v_cvt_pk_bf16_f32 v52, v50, v51
	s_nop 1
	v_permlane32_swap_b32_e32 v52, v54
	v_permlane32_swap_b32_e32 v53, v55
	global_store_dwordx4 v[36:37], v[52:55], off offset:64
	v_pk_mul_f32 v[44:45], v[32:33], v[42:43] op_sel_hi:[1,0]
	v_pk_mul_f32 v[46:47], v[30:31], v[42:43] op_sel_hi:[1,0]
	v_pk_mul_f32 v[48:49], v[28:29], v[42:43] op_sel_hi:[1,0]
	v_pk_mul_f32 v[50:51], v[26:27], v[42:43] op_sel_hi:[1,0]
	v_cvt_pk_bf16_f32 v55, v44, v45
	v_cvt_pk_bf16_f32 v54, v46, v47
	v_cvt_pk_bf16_f32 v53, v48, v49
	v_cvt_pk_bf16_f32 v52, v50, v51
	s_nop 1
	v_permlane32_swap_b32_e32 v52, v54
	v_permlane32_swap_b32_e32 v53, v55
	global_store_dwordx4 v[36:37], v[52:55], off offset:96
	s_cmp_lg_u32 s42, 0
	s_cbranch_scc1 .Lat_partB
	s_branch .LBB0_552

; #define LAS __attribute__((address_space(3)))
; __device__ __forceinline__ void attn_phase(LAS unsigned char* lds, const bf16_t* __restrict__ Q, const bf16_t* __restrict__ KN, const bf16_t* __restrict__ KR,
;                                            const bf16_t* __restrict__ VT, bf16_t* AO, int vcu, int G, int tid, int lane, int wave) {
;     ...
;             *(LAS u32x4*)(lds + kdst) = gk0; *(LAS u32x4*)(lds + kdst + 64 * KP * 2) = gk1; *(LAS u32x4*)(lds + rdst) = gr; *(LAS u32x4*)(lds + vdst) = gv0; *(LAS u32x4*)(lds + vdst + 128) = gv1;
;             __syncthreads();
;             float m_run = -INFINITY, l_run = 0.f;
;             f32x16 o0, o1;
; #pragma unroll
;             for (int r = 0; r < 16; ++r) { o0[r] = 0.f; o1[r] = 0.f; }
.Lat_partB:
	v_mov_b32_e32 v2, 0
	v_mov_b32_e32 v3, 0
	v_mov_b32_e32 v4, 0
	v_mov_b32_e32 v5, 0
	v_mov_b32_e32 v6, 0
	v_mov_b32_e32 v7, 0
	v_mov_b32_e32 v8, 0
	v_mov_b32_e32 v9, 0
	v_mov_b32_e32 v10, 0
	v_mov_b32_e32 v11, 0
	v_mov_b32_e32 v12, 0
	v_mov_b32_e32 v13, 0
	v_mov_b32_e32 v14, 0
	v_mov_b32_e32 v15, 0
	v_mov_b32_e32 v16, 0
	v_mov_b32_e32 v17, 0
	v_mov_b32_e32 v18, 0
	v_mov_b32_e32 v19, 0
	v_mov_b32_e32 v20, 0
	v_mov_b32_e32 v21, 0
	v_mov_b32_e32 v22, 0
	v_mov_b32_e32 v23, 0
	v_mov_b32_e32 v24, 0
	v_mov_b32_e32 v25, 0
	v_mov_b32_e32 v26, 0
	v_mov_b32_e32 v27, 0
	v_mov_b32_e32 v28, 0
	v_mov_b32_e32 v29, 0
	v_mov_b32_e32 v30, 0
	v_mov_b32_e32 v31, 0
	v_mov_b32_e32 v32, 0
	v_mov_b32_e32 v33, 0
	v_mov_b32_e32 v98, 0
	v_mov_b32_e32 v99, 0
	v_mov_b32_e32 v100, 0
	v_mov_b32_e32 v101, 0
	v_mov_b32_e32 v102, 0
	v_mov_b32_e32 v103, 0
	v_mov_b32_e32 v104, 0
	v_mov_b32_e32 v105, 0
	v_mov_b32_e32 v106, 0
	v_mov_b32_e32 v107, 0
	v_mov_b32_e32 v108, 0
	v_mov_b32_e32 v109, 0
	v_mov_b32_e32 v110, 0
	v_mov_b32_e32 v111, 0
	v_mov_b32_e32 v112, 0
	v_mov_b32_e32 v113, 0
	v_mov_b32_e32 v227, 0
	v_mov_b32_e32 v248, 0
	s_add_i32 s36, s36, 2
	s_lshr_b32 s33, s8, 6
	s_mov_b32 s8, 0
	s_mov_b32 s26, 0x4e800000
	s_mov_b32 s27, 0xff7fffff
	s_mov_b32 s6, 0
	s_mov_b32 s7, 1
	v_mov_b32_e32 v218, 0
	s_waitcnt vmcnt(6)
	s_mov_b32 s38, 0
	v_add_u32_e32 v1, s38, v219
	ds_write_b128 v1, v[228:231]
	ds_write_b128 v1, v[232:235] offset:13312
	v_add_u32_e32 v1, s38, v220
	ds_write_b128 v1, v[236:239]
	v_add_u32_e32 v1, s38, v221
	ds_write_b128 v1, v[240:243] offset:26624
	ds_write_b128 v1, v[244:247] offset:26752
	s_waitcnt lgkmcnt(0)
	s_barrier
